# mixer queue order 2: 40 long other-FoX items before the mLSTM output items, the last 128 stick-breaking items moved to the queue tail
# speedup vs baseline: 1.0090x; 1.0004x over previous
; __global__ void __launch_bounds__(512, 2) mega_fwd(Args a) {
;     ...
;                 int it = 0; if (lane == 0) it = (int)atomicAdd(ctr, 1u); it = __builtin_amdgcn_readfirstlane(it) * 8 + sq;
;                 if (it >= 874) break;
;                 if (it < 138) {
;                     if (it >= 48) { __builtin_amdgcn_s_setprio(3); mlstm_item<false>(ub, yb, mscr, prm + 512, prm + 8, prm + 16, prm + 64, L + wave * ML_WSTRIDE, xcd + 8 * ((it - 48) / 15), (it - 48) % 15, lane); __builtin_amdgcn_s_setprio(0); }
;                     else fox_cumsum_item(ub, prm, fcl, ftot, (xcd + 8 * (it >> 3)) * 8 + (it & 7), lane);
;                     asm volatile("s_waitcnt vmcnt(0)" ::: "memory");
;                     if (lane == 0) atomicAdd(done + (it >= 48 ? 8 : 0), 1u);
;                 } else {
;                     const bool issb = (it >= 266 && it < 522), isc = (it >= 522 && it < 618), isfox = !isc && !issb;
;                     if (isfox && !((okmask >> xcd) & 1u)) { unsigned sp = 0u;
;                         while (__hip_atomic_load(done, __ATOMIC_RELAXED, __HIP_MEMORY_SCOPE_AGENT) < 48u) { __builtin_amdgcn_s_sleep(120); if (++sp > (1u << 17)) break; }
;                         __builtin_amdgcn_fence(__ATOMIC_ACQUIRE, "agent"); okmask |= 1u << xcd; }
;                     if (isc && !((okmask >> (8 + xcd)) & 1u)) { unsigned sp = 0u;
;                         while (__hip_atomic_load(done + 8, __ATOMIC_RELAXED, __HIP_MEMORY_SCOPE_AGENT) < 90u) { __builtin_amdgcn_s_sleep(120); if (++sp > (1u << 17)) break; }
;                         __builtin_amdgcn_fence(__ATOMIC_ACQUIRE, "agent"); okmask |= 1u << (8 + xcd); }
;                     if (isc) { const int ci = it - 522; __builtin_amdgcn_s_setprio(2); mlstm_item<true>(ub, yb, mscr, prm + 512, prm + 8, prm + 16, prm + 64, L + wave * ML_WSTRIDE, xcd + 8 * (ci >> 4), 15 - (ci & 15), lane); __builtin_amdgcn_s_setprio(0); }
;                     else { int aitem; if (issb) { const int ai = it - 266; aitem = (ai >> 2) * 80 + 48 + xcd + 8 * (ai & 3); } else { const int ai = (it < 266) ? it - 138 : it - 490; aitem = (ai / 6) * 80 + xcd + 8 * (ai % 6); }
;                         attn_mfma_item(ub, yb, fcl, ftot, L + wave * ML_WSTRIDE, aitem, lane); }
.LBB0_711:
	s_or_b64 exec, exec, s[0:1]
	v_readfirstlane_b32 s2, v1
	s_lshl_b32 s0, s2, 3
	v_readlane_b32 s1, v255, 13
	s_or_b32 s98, s0, s1
	s_cmpk_gt_i32 s98, 0x369
	s_cselect_b64 s[0:1], -1, 0
	s_and_b64 vcc, exec, s[0:1]
	s_cbranch_vccnz .LBB0_706
	s_cmpk_lt_i32 s98, 0x8a
	s_cbranch_scc1 .Lq_noremap
	s_cmpk_gt_i32 s98, 0x189
	s_cbranch_scc1 .Lq_remap2
	s_movk_i32 s3, 0x80
	s_cmpk_lt_i32 s98, 0x10a
	s_cselect_b32 s3, s3, 0xffffff80
	s_add_i32 s98, s98, s3
	s_branch .Lq_noremap
.Lq_remap2:
	s_movk_i32 s3, 0xe0
	s_cmpk_lt_i32 s98, 0x1b2
	s_cbranch_scc1 .Lq_add
	s_movk_i32 s3, 0x58
	s_cmpk_lt_i32 s98, 0x212
	s_cbranch_scc1 .Lq_add
	s_movk_i32 s3, 0x80
	s_cmpk_lt_i32 s98, 0x2ea
	s_cbranch_scc1 .Lq_add
	s_movk_i32 s3, 0xfea0
.Lq_add:
	s_add_i32 s98, s98, s3
